# MLA attention loop: softmax exponent arguments via v_pk_fma_f32 pairs (f32, same math)
# baseline (speedup 1.0000x reference)
.LBB0_592:
	s_cmp_lt_u32 s14, s7
	s_cselect_b32 s4, 0, s7
	s_cselect_b32 s5, s24, s1
	s_lshl_b32 s4, s4, 5
	s_sub_i32 s4, s5, s4
	s_add_i32 s30, s15, s4
	s_add_i32 s4, s10, s14
	v_add_u32_e32 v66, s30, v158
	s_cmp_lt_u32 s4, s7
	v_ashrrev_i32_e32 v67, 31, v66
	s_cselect_b32 s4, 0, s7
	v_lshlrev_b64 v[66:67], 9, v[66:67]
	s_cselect_b32 s5, s24, s1
	s_lshl_b32 s4, s4, 5
	v_add_u32_e32 v166, 0x8800, v161
	v_add_u32_e32 v167, 0xac00, v161
	v_add_u32_e32 v168, 0xd000, v161
	v_add_u32_e32 v169, 0xf400, v161
	v_lshl_add_u64 v[66:67], v[150:151], 0, v[66:67]
	s_sub_i32 s4, s5, s4
	s_add_i32 s5, s20, s15
	s_waitcnt vmcnt(7)
	ds_write_b128 v160, v[118:121]
	s_waitcnt vmcnt(6)
	ds_write2_b64 v166, v[114:115], v[116:117] offset1:1
	s_waitcnt vmcnt(5)
	ds_write_b128 v160, v[126:129] offset:8704
	s_waitcnt vmcnt(4)
	ds_write2_b64 v167, v[122:123], v[124:125] offset1:1
	s_waitcnt vmcnt(3)
	ds_write_b128 v160, v[134:137] offset:17408
	s_waitcnt vmcnt(2)
	ds_write2_b64 v168, v[130:131], v[132:133] offset1:1
	s_waitcnt vmcnt(1)
	ds_write_b128 v160, v[142:145] offset:26112
	s_waitcnt vmcnt(0)
	ds_write2_b64 v169, v[138:139], v[140:141] offset1:1
	s_waitcnt lgkmcnt(0)
	s_barrier
	global_load_dwordx4 v[118:121], v[66:67], off
	v_lshl_add_u64 v[66:67], s[30:31], 1, v[152:153]
	s_add_i32 s30, s5, s4
	s_add_i32 s4, s4, s15
	global_load_dwordx4 v[114:117], v[66:67], off
	v_add_u32_e32 v66, s4, v164
	s_add_i32 s4, s11, s14
	s_cmp_lt_u32 s4, s7
	v_ashrrev_i32_e32 v67, 31, v66
	s_cselect_b32 s4, 0, s7
	v_lshlrev_b64 v[66:67], 9, v[66:67]
	s_cselect_b32 s5, s24, s1
	s_lshl_b32 s4, s4, 5
	v_lshl_add_u64 v[66:67], v[150:151], 0, v[66:67]
	s_sub_i32 s4, s5, s4
	s_add_i32 s5, s21, s15
	global_load_dwordx4 v[126:129], v[66:67], off
	v_lshl_add_u64 v[66:67], s[30:31], 1, v[152:153]
	s_add_i32 s30, s5, s4
	s_add_i32 s4, s4, s15
	global_load_dwordx4 v[122:125], v[66:67], off
	v_add_u32_e32 v66, s4, v162
	s_add_i32 s4, s18, s14
	s_cmp_lt_u32 s4, s7
	v_ashrrev_i32_e32 v67, 31, v66
	s_cselect_b32 s4, 0, s7
	v_lshlrev_b64 v[66:67], 9, v[66:67]
	s_cselect_b32 s5, s24, s1
	s_lshl_b32 s4, s4, 5
	v_lshl_add_u64 v[66:67], v[150:151], 0, v[66:67]
	s_sub_i32 s4, s5, s4
	s_add_i32 s5, s19, s15
	global_load_dwordx4 v[134:137], v[66:67], off
	v_lshl_add_u64 v[66:67], s[30:31], 1, v[152:153]
	s_add_i32 s30, s5, s4
	s_add_i32 s4, s4, s15
	global_load_dwordx4 v[130:133], v[66:67], off
	v_add_u32_e32 v66, s4, v163
	v_ashrrev_i32_e32 v67, 31, v66
	v_lshlrev_b64 v[66:67], 9, v[66:67]
	v_lshl_add_u64 v[66:67], v[150:151], 0, v[66:67]
	global_load_dwordx4 v[142:145], v[66:67], off
	v_lshl_add_u64 v[66:67], s[30:31], 1, v[152:153]
	global_load_dwordx4 v[138:141], v[66:67], off
	ds_read_b128 v[66:69], v159
	ds_read_b128 v[176:179], v159 offset:32
	s_waitcnt lgkmcnt(1)
	v_mfma_f32_32x32x16_bf16 v[66:81], v[66:69], v[110:113], 0
	v_mov_b32_e32 v0, v149
	v_mov_b32_e32 v175, v148
	s_add_i32 s15, s15, 32
	s_add_i32 s14, s14, 1
	s_cmp_lg_u32 s20, s15
	s_waitcnt lgkmcnt(0)
	v_mfma_f32_32x32x16_bf16 v[66:81], v[176:179], v[106:109], v[66:81]
	ds_read_b128 v[176:179], v159 offset:64
	s_waitcnt lgkmcnt(0)
	v_mfma_f32_32x32x16_bf16 v[66:81], v[176:179], v[102:105], v[66:81]
	ds_read_b128 v[176:179], v159 offset:96
	s_waitcnt lgkmcnt(0)
	v_mfma_f32_32x32x16_bf16 v[66:81], v[176:179], v[98:101], v[66:81]
	ds_read_b128 v[176:179], v159 offset:128
	s_waitcnt lgkmcnt(0)
	v_mfma_f32_32x32x16_bf16 v[66:81], v[176:179], v[94:97], v[66:81]
	ds_read_b128 v[176:179], v159 offset:160
	s_waitcnt lgkmcnt(0)
	v_mfma_f32_32x32x16_bf16 v[66:81], v[176:179], v[90:93], v[66:81]
	ds_read_b128 v[176:179], v159 offset:192
	s_waitcnt lgkmcnt(0)
	v_mfma_f32_32x32x16_bf16 v[66:81], v[176:179], v[86:89], v[66:81]
	ds_read_b128 v[176:179], v159 offset:224
	s_waitcnt lgkmcnt(0)
	v_mfma_f32_32x32x16_bf16 v[66:81], v[176:179], v[82:85], v[66:81]
	s_nop 11
	v_max_f32_e32 v148, v67, v67
	v_max_f32_e32 v149, v66, v66
	v_max_f32_e32 v148, v149, v148
	v_max3_f32 v148, v148, v68, v69
	v_max3_f32 v148, v148, v70, v71
	v_max3_f32 v148, v148, v72, v73
	v_max3_f32 v148, v148, v74, v75
	v_max3_f32 v148, v148, v76, v77
	v_max3_f32 v148, v148, v78, v79
	v_max3_f32 v148, v148, v80, v81
	v_mov_b32_e32 v149, v148
	s_nop 1
	v_permlane32_swap_b32 v149, v148
	s_waitcnt lgkmcnt(0)
	v_max3_f32 v149, v0, v148, v149
	v_mov_b32_e32 v148, v81
	v_pk_mul_f32 v[176:177], v[148:149], s[28:29] op_sel_hi:[1,0]
	v_sub_f32_e32 v0, v0, v149
	v_pk_fma_f32 v[70:71], v[70:71], s[28:29], v[176:177] op_sel:[0,0,1] op_sel_hi:[1,0,1] neg_lo:[0,0,1] neg_hi:[0,0,1]
	v_pk_fma_f32 v[72:73], v[72:73], s[28:29], v[176:177] op_sel:[0,0,1] op_sel_hi:[1,0,1] neg_lo:[0,0,1] neg_hi:[0,0,1]
	v_exp_f32_e32 v81, v70
	v_exp_f32_e32 v178, v71
	v_pk_fma_f32 v[74:75], v[74:75], s[28:29], v[176:177] op_sel:[0,0,1] op_sel_hi:[1,0,1] neg_lo:[0,0,1] neg_hi:[0,0,1]
	v_exp_f32_e32 v179, v72
	v_exp_f32_e32 v73, v73
	v_pk_fma_f32 v[76:77], v[76:77], s[28:29], v[176:177] op_sel:[0,0,1] op_sel_hi:[1,0,1] neg_lo:[0,0,1] neg_hi:[0,0,1]
	v_exp_f32_e32 v74, v74
	v_exp_f32_e32 v75, v75
	v_pk_fma_f32 v[66:67], v[66:67], s[28:29], v[176:177] op_sel:[0,0,1] op_sel_hi:[1,0,1] neg_lo:[0,0,1] neg_hi:[0,0,1]
	v_exp_f32_e32 v76, v76
	v_exp_f32_e32 v77, v77
	v_pk_fma_f32 v[68:69], v[68:69], s[28:29], v[176:177] op_sel:[0,0,1] op_sel_hi:[1,0,1] neg_lo:[0,0,1] neg_hi:[0,0,1]
	v_exp_f32_e32 v66, v66
	v_exp_f32_e32 v67, v67
	v_pk_fma_f32 v[78:79], v[78:79], s[28:29], v[176:177] op_sel:[0,0,1] op_sel_hi:[1,0,1] neg_lo:[0,0,1] neg_hi:[0,0,1]
	v_exp_f32_e32 v68, v68
	v_exp_f32_e32 v69, v69
	v_fma_f32 v80, v80, s28, -v177
	v_exp_f32_e32 v78, v78
	v_exp_f32_e32 v79, v79
	v_exp_f32_e32 v80, v80
	v_sub_f32_e32 v70, v176, v177
	v_exp_f32_e32 v176, v70
	v_add_f32_e32 v70, 0, v66
	v_add_f32_e32 v70, v67, v70
	v_add_f32_e32 v70, v68, v70
	v_add_f32_e32 v70, v69, v70
	v_add_f32_e32 v70, v81, v70
	v_add_f32_e32 v70, v178, v70
	v_add_f32_e32 v70, v179, v70
	v_add_f32_e32 v70, v73, v70
	v_add_f32_e32 v70, v74, v70
	v_add_f32_e32 v70, v75, v70
	v_add_f32_e32 v70, v76, v70
	v_add_f32_e32 v70, v77, v70
	v_add_f32_e32 v70, v78, v70
	v_mul_f32_e32 v0, 0x3e0293ee, v0
	v_add_f32_e32 v70, v79, v70
	v_exp_f32_e32 v0, v0
	v_add_f32_e32 v70, v80, v70
	v_cvt_pk_bf16_f32 v73, v179, v73
	v_add_u32_e32 v179, 0x8800, v165
	v_add_f32_e32 v148, v176, v70
	v_cvt_pk_bf16_f32 v70, v66, v67
	v_cvt_pk_bf16_f32 v71, v68, v69
	v_cvt_pk_bf16_f32 v72, v81, v178
	v_cvt_pk_bf16_f32 v66, v74, v75
	v_cvt_pk_bf16_f32 v67, v76, v77
	v_cvt_pk_bf16_f32 v68, v78, v79
	v_cvt_pk_bf16_f32 v69, v80, v176
	ds_read2_b64 v[74:77], v179 offset1:2
	ds_read2_b64 v[78:81], v179 offset0:4 offset1:6
	v_pk_mul_f32 v[64:65], v[64:65], v[0:1] op_sel_hi:[1,0]
	v_pk_mul_f32 v[62:63], v[62:63], v[0:1] op_sel_hi:[1,0]
	v_pk_mul_f32 v[60:61], v[60:61], v[0:1] op_sel_hi:[1,0]
	v_pk_mul_f32 v[58:59], v[58:59], v[0:1] op_sel_hi:[1,0]
	v_pk_mul_f32 v[56:57], v[56:57], v[0:1] op_sel_hi:[1,0]
	v_pk_mul_f32 v[54:55], v[54:55], v[0:1] op_sel_hi:[1,0]
	v_pk_mul_f32 v[52:53], v[52:53], v[0:1] op_sel_hi:[1,0]
	v_pk_mul_f32 v[50:51], v[50:51], v[0:1] op_sel_hi:[1,0]
	v_add_u32_e32 v176, 0x9000, v165
	v_pk_mul_f32 v[48:49], v[48:49], v[0:1] op_sel_hi:[1,0]
	s_waitcnt lgkmcnt(1)
	v_mfma_f32_32x32x16_bf16 v[50:65], v[74:77], v[70:73], v[50:65]
	ds_read2_b64 v[74:77], v176 offset0:32 offset1:34
	v_mul_f32_e64 v46, v46, v0
	v_mul_f32_e64 v47, v47, v0
	v_mul_f32_e64 v44, v44, v0
	v_mul_f32_e64 v45, v45, v0
	v_pk_mul_f32 v[42:43], v[42:43], v[0:1] op_sel_hi:[1,0]
	v_pk_mul_f32 v[40:41], v[40:41], v[0:1] op_sel_hi:[1,0]
	v_pk_mul_f32 v[38:39], v[38:39], v[0:1] op_sel_hi:[1,0]
	v_pk_mul_f32 v[36:37], v[36:37], v[0:1] op_sel_hi:[1,0]
	v_pk_mul_f32 v[34:35], v[34:35], v[0:1] op_sel_hi:[1,0]
	v_add_u32_e32 v177, 0x9800, v165
	v_pk_mul_f32 v[32:33], v[32:33], v[0:1] op_sel_hi:[1,0]
	s_waitcnt lgkmcnt(0)
	v_mfma_f32_32x32x16_bf16 v[34:49], v[74:77], v[70:73], v[34:49]
	ds_read2_b64 v[74:77], v176 offset0:36 offset1:38
	v_mul_f32_e64 v30, v30, v0
	v_mul_f32_e64 v31, v31, v0
	v_mul_f32_e64 v28, v28, v0
	v_mul_f32_e64 v29, v29, v0
	v_pk_mul_f32 v[26:27], v[26:27], v[0:1] op_sel_hi:[1,0]
	v_pk_mul_f32 v[24:25], v[24:25], v[0:1] op_sel_hi:[1,0]
	v_pk_mul_f32 v[22:23], v[22:23], v[0:1] op_sel_hi:[1,0]
	v_pk_mul_f32 v[20:21], v[20:21], v[0:1] op_sel_hi:[1,0]
	s_waitcnt lgkmcnt(0)
	v_mfma_f32_32x32x16_bf16 v[34:49], v[74:77], v[66:69], v[34:49]
	ds_read2_b64 v[74:77], v177 offset0:64 offset1:66
	v_mul_f32_e64 v18, v18, v0
	v_mul_f32_e64 v19, v19, v0
	v_add_u32_e32 v178, 0xa000, v165
	v_mul_f32_e64 v16, v16, v0
	v_mul_f32_e64 v17, v17, v0
	v_pk_mul_f32 v[14:15], v[14:15], v[0:1] op_sel_hi:[1,0]
	v_pk_mul_f32 v[12:13], v[12:13], v[0:1] op_sel_hi:[1,0]
	v_pk_mul_f32 v[10:11], v[10:11], v[0:1] op_sel_hi:[1,0]
	s_waitcnt lgkmcnt(0)
	v_mfma_f32_32x32x16_bf16 v[18:33], v[74:77], v[70:73], v[18:33]
	ds_read2_b64 v[74:77], v177 offset0:68 offset1:70
	v_mul_f32_e64 v8, v8, v0
	v_mul_f32_e64 v9, v9, v0
	v_mul_f32_e64 v6, v6, v0
	v_mul_f32_e64 v7, v7, v0
	v_pk_mul_f32 v[4:5], v[4:5], v[0:1] op_sel_hi:[1,0]
	v_pk_mul_f32 v[2:3], v[2:3], v[0:1] op_sel_hi:[1,0]
	v_fmac_f32_e32 v148, v175, v0
	s_waitcnt lgkmcnt(0)
	v_mfma_f32_32x32x16_bf16 v[18:33], v[74:77], v[66:69], v[18:33]
	ds_read2_b64 v[74:77], v178 offset0:96 offset1:98
	s_waitcnt lgkmcnt(0)
	v_mfma_f32_32x32x16_bf16 v[2:17], v[74:77], v[70:73], v[2:17]
	ds_read2_b64 v[70:73], v178 offset0:100 offset1:102
	s_waitcnt lgkmcnt(0)
	s_barrier
	v_mfma_f32_32x32x16_bf16 v[50:65], v[78:81], v[66:69], v[50:65]
	v_mfma_f32_32x32x16_bf16 v[2:17], v[70:73], v[66:69], v[2:17]
	s_cbranch_scc1 .LBB0_592
	s_waitcnt vmcnt(7)
	ds_write_b128 v160, v[118:121]
	s_waitcnt vmcnt(6)
	ds_write2_b64 v166, v[114:115], v[116:117] offset1:1
	s_waitcnt vmcnt(5)
	ds_write_b128 v160, v[126:129] offset:8704
	s_waitcnt vmcnt(4)
	ds_write2_b64 v167, v[122:123], v[124:125] offset1:1
	s_waitcnt vmcnt(3)
	ds_write_b128 v160, v[134:137] offset:17408
	s_waitcnt vmcnt(2)
	ds_write2_b64 v168, v[130:131], v[132:133] offset1:1
	s_waitcnt vmcnt(1)
	ds_write_b128 v160, v[142:145] offset:26112
	s_waitcnt vmcnt(0)
	ds_write2_b64 v169, v[138:139], v[140:141] offset1:1
	s_waitcnt lgkmcnt(0)
	s_barrier
	ds_read_b128 v[66:69], v159
	ds_read_b128 v[114:117], v159 offset:32
	s_waitcnt lgkmcnt(1)
	v_mfma_f32_32x32x16_bf16 v[66:81], v[66:69], v[110:113], 0
	v_readlane_b32 s1, v253, 17
	s_mov_b32 s4, 0xf149f2ca
	s_waitcnt lgkmcnt(0)
	v_mfma_f32_32x32x16_bf16 v[66:81], v[114:117], v[106:109], v[66:81]
	ds_read_b128 v[106:109], v159 offset:64
	ds_read_b128 v[110:113], v159 offset:96
	s_waitcnt lgkmcnt(1)
	v_mfma_f32_32x32x16_bf16 v[66:81], v[106:109], v[102:105], v[66:81]
	s_waitcnt lgkmcnt(0)
	v_mfma_f32_32x32x16_bf16 v[66:81], v[110:113], v[98:101], v[66:81]
	ds_read_b128 v[98:101], v159 offset:128
	ds_read_b128 v[102:105], v159 offset:160
	s_waitcnt lgkmcnt(1)
	v_mfma_f32_32x32x16_bf16 v[66:81], v[98:101], v[94:97], v[66:81]
	v_ashrrev_i32_e32 v100, 6, v157
	s_waitcnt lgkmcnt(0)
	v_mfma_f32_32x32x16_bf16 v[66:81], v[102:105], v[90:93], v[66:81]
	ds_read_b128 v[90:93], v159 offset:192
	ds_read_b128 v[94:97], v159 offset:224
	s_waitcnt lgkmcnt(1)
	v_mfma_f32_32x32x16_bf16 v[66:81], v[90:93], v[86:89], v[66:81]
	ds_read2_b64 v[86:89], v179 offset1:2
	s_waitcnt lgkmcnt(1)
	v_mfma_f32_32x32x16_bf16 v[66:81], v[94:97], v[82:85], v[66:81]
	ds_read2_b64 v[90:93], v179 offset0:4 offset1:6
	ds_read2_b64 v[94:97], v176 offset0:32 offset1:34
	s_nop 9
	v_max_f32_e32 v0, v67, v67
	v_max_f32_e32 v82, v66, v66
	v_max_f32_e32 v0, v82, v0
	v_max3_f32 v0, v0, v68, v69
	v_max3_f32 v0, v0, v70, v71
	v_max3_f32 v0, v0, v72, v73
	v_max3_f32 v0, v0, v74, v75
	v_max3_f32 v0, v0, v76, v77
	v_max3_f32 v0, v0, v78, v79
	v_max3_f32 v0, v0, v80, v81
	v_mov_b32_e32 v83, v0
	v_mov_b32_e32 v84, v81
	v_and_b32_e32 v82, 1, v100
	v_permlane32_swap_b32 v83, v0
	s_waitcnt lgkmcnt(0)
	v_max3_f32 v85, v149, v0, v83
	v_sub_f32_e32 v0, v149, v85
	v_pk_mul_f32 v[98:99], v[84:85], s[28:29] op_sel_hi:[1,0]
	v_mul_f32_e32 v0, 0x3e0293ee, v0
	v_fma_f32 v66, v66, s28, -v99
	v_fma_f32 v67, v67, s28, -v99
	v_fma_f32 v68, v68, s28, -v99
	v_fma_f32 v69, v69, s28, -v99
	v_fma_f32 v70, v70, s28, -v99
	v_fma_f32 v71, v71, s28, -v99
	v_fma_f32 v72, v72, s28, -v99
	v_fma_f32 v73, v73, s28, -v99
	v_fma_f32 v74, v74, s28, -v99
	v_fma_f32 v75, v75, s28, -v99
	v_fma_f32 v76, v76, s28, -v99
	v_fma_f32 v77, v77, s28, -v99
	v_fma_f32 v78, v78, s28, -v99
	v_fma_f32 v79, v79, s28, -v99
	v_fma_f32 v80, v80, s28, -v99
	v_sub_f32_e32 v81, v98, v99
	v_exp_f32_e32 v0, v0
	v_exp_f32_e32 v83, v66
	v_exp_f32_e32 v84, v67
	v_exp_f32_e32 v98, v68
	v_exp_f32_e32 v99, v69
	v_exp_f32_e32 v101, v70
	v_exp_f32_e32 v102, v71
	v_exp_f32_e32 v103, v72
	v_exp_f32_e32 v104, v73
	v_exp_f32_e32 v105, v74
	v_exp_f32_e32 v106, v75
	v_exp_f32_e32 v107, v76
	v_exp_f32_e32 v108, v77
	v_pk_mul_f32 v[48:49], v[48:49], v[0:1] op_sel_hi:[1,0]
	v_pk_mul_f32 v[46:47], v[46:47], v[0:1] op_sel_hi:[1,0]
	v_cvt_pk_bf16_f32 v66, v83, v84
	v_cvt_pk_bf16_f32 v67, v98, v99
	v_cvt_pk_bf16_f32 v68, v101, v102
	v_cvt_pk_bf16_f32 v69, v103, v104
	v_pk_mul_f32 v[44:45], v[44:45], v[0:1] op_sel_hi:[1,0]
	v_pk_mul_f32 v[42:43], v[42:43], v[0:1] op_sel_hi:[1,0]
	v_pk_mul_f32 v[40:41], v[40:41], v[0:1] op_sel_hi:[1,0]
	v_pk_mul_f32 v[38:39], v[38:39], v[0:1] op_sel_hi:[1,0]
	v_pk_mul_f32 v[36:37], v[36:37], v[0:1] op_sel_hi:[1,0]
	v_pk_mul_f32 v[34:35], v[34:35], v[0:1] op_sel_hi:[1,0]
	ds_read2_b64 v[74:77], v176 offset0:36 offset1:38
	v_exp_f32_e32 v109, v78
	v_exp_f32_e32 v110, v79
	v_exp_f32_e32 v111, v80
	v_exp_f32_e32 v112, v81
	v_mfma_f32_32x32x16_bf16 v[34:49], v[94:97], v[66:69], v[34:49]
	ds_read2_b64 v[78:81], v177 offset0:64 offset1:66
	v_cvt_pk_bf16_f32 v70, v105, v106
	v_cvt_pk_bf16_f32 v71, v107, v108
	v_cvt_pk_bf16_f32 v72, v109, v110
	v_cvt_pk_bf16_f32 v73, v111, v112
	v_pk_mul_f32 v[32:33], v[32:33], v[0:1] op_sel_hi:[1,0]
	v_pk_mul_f32 v[30:31], v[30:31], v[0:1] op_sel_hi:[1,0]
	v_pk_mul_f32 v[28:29], v[28:29], v[0:1] op_sel_hi:[1,0]
	v_pk_mul_f32 v[26:27], v[26:27], v[0:1] op_sel_hi:[1,0]
	v_pk_mul_f32 v[24:25], v[24:25], v[0:1] op_sel_hi:[1,0]
	v_pk_mul_f32 v[22:23], v[22:23], v[0:1] op_sel_hi:[1,0]
	v_pk_mul_f32 v[20:21], v[20:21], v[0:1] op_sel_hi:[1,0]
	v_pk_mul_f32 v[18:19], v[18:19], v[0:1] op_sel_hi:[1,0]
	s_waitcnt lgkmcnt(1)
	v_mfma_f32_32x32x16_bf16 v[34:49], v[74:77], v[70:73], v[34:49]
	ds_read2_b64 v[74:77], v177 offset0:68 offset1:70
	v_mul_f32_e64 v64, v64, v0
	v_mul_f32_e64 v65, v65, v0
	v_mul_f32_e64 v62, v62, v0
	v_mul_f32_e64 v63, v63, v0
	v_pk_mul_f32 v[60:61], v[60:61], v[0:1] op_sel_hi:[1,0]
	v_pk_mul_f32 v[58:59], v[58:59], v[0:1] op_sel_hi:[1,0]
	v_pk_mul_f32 v[56:57], v[56:57], v[0:1] op_sel_hi:[1,0]
	v_pk_mul_f32 v[54:55], v[54:55], v[0:1] op_sel_hi:[1,0]
	s_waitcnt lgkmcnt(1)
	v_mfma_f32_32x32x16_bf16 v[18:33], v[78:81], v[66:69], v[18:33]
	v_add_f32_e32 v78, 0, v83
	v_add_f32_e32 v78, v84, v78
	v_add_f32_e32 v78, v98, v78
	v_add_f32_e32 v78, v99, v78
	v_add_f32_e32 v83, v101, v78
	ds_read2_b64 v[78:81], v178 offset0:96 offset1:98
	v_pk_mul_f32 v[52:53], v[52:53], v[0:1] op_sel_hi:[1,0]
	s_waitcnt lgkmcnt(1)
	v_mfma_f32_32x32x16_bf16 v[18:33], v[74:77], v[70:73], v[18:33]
	v_add_f32_e32 v74, v102, v83
	v_add_f32_e32 v74, v103, v74
	v_add_f32_e32 v74, v104, v74
	v_add_f32_e32 v74, v105, v74
	v_mul_f32_e64 v50, v50, v0
	v_mul_f32_e64 v51, v51, v0
	v_add_f32_e32 v74, v106, v74
	v_pk_mul_f32 v[16:17], v[16:17], v[0:1] op_sel_hi:[1,0]
	v_mfma_f32_32x32x16_bf16 v[50:65], v[86:89], v[66:69], v[50:65]
	v_mul_f32_e64 v14, v14, v0
	v_mul_f32_e64 v15, v15, v0
	v_mul_f32_e64 v12, v12, v0
	v_mul_f32_e64 v13, v13, v0
	v_mul_f32_e64 v10, v10, v0
	v_mul_f32_e64 v11, v11, v0
	v_pk_mul_f32 v[8:9], v[8:9], v[0:1] op_sel_hi:[1,0]
	v_pk_mul_f32 v[6:7], v[6:7], v[0:1] op_sel_hi:[1,0]
	v_pk_mul_f32 v[4:5], v[4:5], v[0:1] op_sel_hi:[1,0]
	v_pk_mul_f32 v[2:3], v[2:3], v[0:1] op_sel_hi:[1,0]
	v_add_f32_e32 v83, v107, v74
	ds_read2_b64 v[74:77], v178 offset0:100 offset1:102
	s_waitcnt lgkmcnt(1)
	v_mfma_f32_32x32x16_bf16 v[2:17], v[78:81], v[66:69], v[2:17]
	v_add_f32_e32 v66, v108, v83
	v_add_f32_e32 v66, v109, v66
	v_add_f32_e32 v66, v110, v66
	v_add_f32_e32 v66, v111, v66
	v_add_f32_e32 v66, v112, v66
	v_fmac_f32_e32 v66, v148, v0
	v_mov_b32_e32 v0, v66
	v_mfma_f32_32x32x16_bf16 v[50:65], v[90:93], v[70:73], v[50:65]
	v_lshlrev_b32_e32 v67, 2, v155
	s_nop 1
	v_permlane32_swap_b32 v0, v66
	s_waitcnt lgkmcnt(0)
	s_barrier
	v_add_f32_e32 v0, v66, v0
	v_lshlrev_b32_e32 v66, 9, v100
	v_add3_u32 v66, s1, v66, v67
	ds_write2st64_b32 v66, v85, v0 offset1:1
	v_lshlrev_b32_e32 v0, 14, v100
	v_add3_u32 v0, 0, v0, v67
	v_mfma_f32_32x32x16_bf16 v[2:17], v[74:77], v[70:73], v[2:17]
	s_nop 1
	ds_write2st64_b32 v0, v50, v51 offset1:1
	ds_write2st64_b32 v0, v52, v53 offset0:2 offset1:3
	ds_write2st64_b32 v0, v54, v55 offset0:4 offset1:5
	ds_write2st64_b32 v0, v56, v57 offset0:6 offset1:7
	ds_write2st64_b32 v0, v58, v59 offset0:8 offset1:9
	ds_write2st64_b32 v0, v60, v61 offset0:10 offset1:11
	ds_write2st64_b32 v0, v62, v63 offset0:12 offset1:13
	ds_write2st64_b32 v0, v64, v65 offset0:14 offset1:15
	ds_write2st64_b32 v0, v34, v35 offset0:16 offset1:17
	ds_write2st64_b32 v0, v36, v37 offset0:18 offset1:19
	ds_write2st64_b32 v0, v38, v39 offset0:20 offset1:21
	ds_write2st64_b32 v0, v40, v41 offset0:22 offset1:23
	ds_write2st64_b32 v0, v42, v43 offset0:24 offset1:25
	ds_write2st64_b32 v0, v44, v45 offset0:26 offset1:27
	ds_write2st64_b32 v0, v46, v47 offset0:28 offset1:29
	ds_write2st64_b32 v0, v48, v49 offset0:30 offset1:31
	ds_write2st64_b32 v0, v18, v19 offset0:32 offset1:33
	ds_write2st64_b32 v0, v20, v21 offset0:34 offset1:35
	ds_write2st64_b32 v0, v22, v23 offset0:36 offset1:37
	ds_write2st64_b32 v0, v24, v25 offset0:38 offset1:39
	ds_write2st64_b32 v0, v26, v27 offset0:40 offset1:41
	ds_write2st64_b32 v0, v28, v29 offset0:42 offset1:43
	ds_write2st64_b32 v0, v30, v31 offset0:44 offset1:45
	ds_write2st64_b32 v0, v32, v33 offset0:46 offset1:47
	ds_write2st64_b32 v0, v2, v3 offset0:48 offset1:49
	ds_write2st64_b32 v0, v4, v5 offset0:50 offset1:51
	ds_write2st64_b32 v0, v6, v7 offset0:52 offset1:53
	ds_write2st64_b32 v0, v8, v9 offset0:54 offset1:55
	ds_write2st64_b32 v0, v10, v11 offset0:56 offset1:57
	ds_write2st64_b32 v0, v12, v13 offset0:58 offset1:59
	ds_write2st64_b32 v0, v14, v15 offset0:60 offset1:61
	ds_write2st64_b32 v0, v16, v17 offset0:62 offset1:63
	v_lshlrev_b32_e32 v0, 9, v82
	v_add3_u32 v0, s1, v0, v67
	s_waitcnt lgkmcnt(0)
	s_barrier
	ds_read2st64_b32 v[4:5], v0 offset1:1
	ds_read2st64_b32 v[6:7], v0 offset0:4 offset1:5
	ds_read2st64_b32 v[8:9], v0 offset0:8 offset1:9
	ds_read2st64_b32 v[10:11], v0 offset0:12 offset1:13
	s_mov_b32 s1, s31
	s_lshl_b64 s[0:1], s[0:1], 11
	s_waitcnt lgkmcnt(2)
	v_max3_f32 v0, v4, s4, v6
	s_add_u32 s4, s80, s0
	s_waitcnt lgkmcnt(0)
	v_max3_f32 v0, v0, v8, v10
	v_sub_f32_e32 v2, v4, v0
	v_mul_f32_e32 v2, 0x3e0293ee, v2
	v_exp_f32_e32 v3, v2
	v_sub_f32_e32 v2, v6, v0
	v_mul_f32_e32 v2, 0x3e0293ee, v2
	v_exp_f32_e32 v2, v2
	v_mov_b32_e32 v4, v7
	s_addc_u32 s5, s81, s1
	v_pk_mul_f32 v[6:7], v[4:5], v[2:3]
	v_sub_f32_e32 v4, v8, v0
	v_sub_f32_e32 v0, v10, v0
	v_mul_f32_e32 v4, 0x3e0293ee, v4
	v_mul_f32_e32 v0, 0x3e0293ee, v0
	v_exp_f32_e32 v5, v4
	v_exp_f32_e32 v4, v0
	v_add_f32_e32 v0, 0, v7
	v_mov_b32_e32 v8, v11
	v_add_f32_e32 v0, v6, v0
	v_pk_mul_f32 v[6:7], v[8:9], v[4:5]
	s_nop 0
	v_add_f32_e32 v0, v7, v0
	v_add_f32_e32 v0, v6, v0
	v_div_scale_f32 v6, s[0:1], v0, v0, 1.0
	v_rcp_f32_e32 v7, v6
	s_lshl_b32 s0, s6, 1
	s_add_u32 s0, s4, s0
	s_addc_u32 s1, s5, 0
	v_fma_f32 v8, -v6, v7, 1.0
	v_fmac_f32_e32 v7, v8, v7
	v_div_scale_f32 v8, vcc, 1.0, v0, 1.0
	v_mul_f32_e32 v9, v8, v7
	v_fma_f32 v10, -v6, v9, v8
	v_fmac_f32_e32 v9, v10, v7
	v_fma_f32 v6, -v6, v9, v8
	v_div_fmas_f32 v6, v6, v7, v9
	v_div_fixup_f32 v0, v6, v0, 1.0
	v_lshl_add_u32 v6, v82, 14, 0
	v_lshlrev_b32_e32 v7, 12, v154
	v_add3_u32 v7, v6, v7, v67
	ds_read2st64_b32 v[8:9], v7 offset1:1
	ds_read2st64_b32 v[10:11], v7 offset0:128 offset1:129
	v_mov_b32_e32 v6, v3
	v_add_u32_e32 v24, 0x10000, v7
	v_add_u32_e32 v25, 0x18000, v7
	v_add_u32_e32 v27, 0x10100, v7
	v_add_u32_e32 v28, 0x18100, v7
	ds_read2st64_b32 v[12:13], v7 offset0:2 offset1:3
	ds_read2st64_b32 v[14:15], v7 offset0:4 offset1:5
	ds_read2st64_b32 v[16:17], v7 offset0:6 offset1:7
	s_waitcnt lgkmcnt(4)
	v_pk_fma_f32 v[8:9], v[8:9], v[6:7], 0 op_sel_hi:[1,0,0]
	v_add_u32_e32 v31, 0x18300, v7
	ds_read2st64_b32 v[18:19], v7 offset0:130 offset1:131
	ds_read2st64_b32 v[20:21], v7 offset0:132 offset1:133
	ds_read2st64_b32 v[22:23], v7 offset0:134 offset1:135
	s_waitcnt lgkmcnt(6)
	v_pk_fma_f32 v[8:9], v[10:11], v[2:3], v[8:9] op_sel_hi:[1,0,1]
	v_mov_b32_e32 v10, v5
	v_add_u32_e32 v3, 0x10200, v7
	v_add_u32_e32 v5, 0x18200, v7
	v_add_u32_e32 v11, 0x10300, v7
	ds_read_b32 v24, v24
	ds_read_b32 v26, v25
	ds_read_b32 v25, v27
	ds_read_b32 v27, v28
	ds_read_b32 v28, v3
	ds_read_b32 v30, v5
	ds_read_b32 v29, v11
	ds_read_b32 v31, v31
	s_waitcnt lgkmcnt(13)
	v_pk_fma_f32 v[12:13], v[6:7], v[12:13], 0 op_sel_hi:[0,1,0]
	s_waitcnt lgkmcnt(5)
	v_pk_fma_f32 v[8:9], v[10:11], v[24:25], v[8:9] op_sel_hi:[0,1,1]
	v_pk_fma_f32 v[12:13], v[2:3], v[18:19], v[12:13] op_sel_hi:[0,1,1]
	v_add_u32_e32 v3, 0x10400, v7
	v_pk_fma_f32 v[14:15], v[6:7], v[14:15], 0 op_sel_hi:[0,1,0]
	s_waitcnt lgkmcnt(4)
	v_pk_fma_f32 v[8:9], v[4:5], v[26:27], v[8:9] op_sel_hi:[0,1,1]
	s_waitcnt lgkmcnt(1)
	v_pk_fma_f32 v[12:13], v[10:11], v[28:29], v[12:13] op_sel_hi:[0,1,1]
	v_add_u32_e32 v11, 0x10500, v7
	v_add_u32_e32 v24, 0x18500, v7
	v_pk_fma_f32 v[14:15], v[2:3], v[20:21], v[14:15] op_sel_hi:[0,1,1]
	v_add_u32_e32 v25, 0x10600, v7
	v_add_u32_e32 v26, 0x18600, v7
	v_add_u32_e32 v27, 0x10700, v7
	s_waitcnt lgkmcnt(0)
	v_pk_fma_f32 v[12:13], v[4:5], v[30:31], v[12:13] op_sel_hi:[0,1,1]
	v_add_u32_e32 v5, 0x18400, v7
	v_add_u32_e32 v28, 0x18700, v7
	ds_read_b32 v18, v3
	ds_read_b32 v20, v5
	ds_read_b32 v19, v11
	ds_read_b32 v21, v24
	ds_read_b32 v24, v25
	ds_read_b32 v26, v26
	ds_read_b32 v25, v27
	ds_read_b32 v27, v28
	s_waitcnt lgkmcnt(5)
	v_pk_fma_f32 v[14:15], v[10:11], v[18:19], v[14:15] op_sel_hi:[0,1,1]
	s_waitcnt lgkmcnt(4)
	v_pk_fma_f32 v[14:15], v[4:5], v[20:21], v[14:15] op_sel_hi:[0,1,1]
	ds_read2st64_b32 v[18:19], v7 offset0:8 offset1:9
	ds_read2st64_b32 v[20:21], v7 offset0:136 offset1:137
	v_pk_fma_f32 v[16:17], v[6:7], v[16:17], 0 op_sel_hi:[0,1,0]
	v_pk_fma_f32 v[16:17], v[2:3], v[22:23], v[16:17] op_sel_hi:[0,1,1]
	s_waitcnt lgkmcnt(3)
	v_pk_fma_f32 v[16:17], v[10:11], v[24:25], v[16:17] op_sel_hi:[0,1,1]
	s_waitcnt lgkmcnt(2)
	v_pk_fma_f32 v[16:17], v[4:5], v[26:27], v[16:17] op_sel_hi:[0,1,1]
	v_add_u32_e32 v3, 0x10800, v7
	v_add_u32_e32 v35, 0x18900, v7
	ds_read2st64_b32 v[22:23], v7 offset0:10 offset1:11
	ds_read2st64_b32 v[24:25], v7 offset0:12 offset1:13
	ds_read2st64_b32 v[26:27], v7 offset0:14 offset1:15
	s_waitcnt lgkmcnt(4)
	v_pk_fma_f32 v[18:19], v[6:7], v[18:19], 0 op_sel_hi:[0,1,0]
	v_add_u32_e32 v36, 0x10a00, v7
	v_add_u32_e32 v37, 0x18a00, v7
	v_add_u32_e32 v39, 0x10b00, v7
	v_add_u32_e32 v5, 0x18800, v7
	v_add_u32_e32 v11, 0x10900, v7
	ds_read2st64_b32 v[28:29], v7 offset0:138 offset1:139
	ds_read2st64_b32 v[30:31], v7 offset0:140 offset1:141
	ds_read2st64_b32 v[32:33], v7 offset0:142 offset1:143
	s_waitcnt lgkmcnt(6)
	v_pk_fma_f32 v[18:19], v[2:3], v[20:21], v[18:19] op_sel_hi:[0,1,1]
	v_add_u32_e32 v40, 0x18b00, v7
	ds_read_b32 v20, v3
	ds_read_b32 v34, v5
	ds_read_b32 v21, v11
	ds_read_b32 v35, v35
	ds_read_b32 v36, v36
	ds_read_b32 v38, v37
	ds_read_b32 v37, v39
	ds_read_b32 v39, v40
	s_waitcnt lgkmcnt(5)
	v_pk_fma_f32 v[18:19], v[10:11], v[20:21], v[18:19] op_sel_hi:[0,1,1]
	v_pk_fma_f32 v[20:21], v[6:7], v[22:23], 0 op_sel_hi:[0,1,0]
	v_pk_fma_f32 v[20:21], v[2:3], v[28:29], v[20:21] op_sel_hi:[0,1,1]
	v_add_u32_e32 v3, 0x10c00, v7
	v_pk_fma_f32 v[22:23], v[6:7], v[24:25], 0 op_sel_hi:[0,1,0]
	s_waitcnt lgkmcnt(4)
	v_pk_fma_f32 v[18:19], v[4:5], v[34:35], v[18:19] op_sel_hi:[0,1,1]
	s_waitcnt lgkmcnt(1)
	v_pk_fma_f32 v[20:21], v[10:11], v[36:37], v[20:21] op_sel_hi:[0,1,1]
	v_add_u32_e32 v29, 0x18d00, v7
	v_pk_fma_f32 v[22:23], v[2:3], v[30:31], v[22:23] op_sel_hi:[0,1,1]
	v_add_u32_e32 v30, 0x10e00, v7
	v_add_u32_e32 v31, 0x18e00, v7
	v_add_u32_e32 v35, 0x10f00, v7
	s_waitcnt lgkmcnt(0)
	v_pk_fma_f32 v[20:21], v[4:5], v[38:39], v[20:21] op_sel_hi:[0,1,1]
	v_add_u32_e32 v5, 0x18c00, v7
	v_add_u32_e32 v11, 0x10d00, v7
	v_add_u32_e32 v7, 0x18f00, v7
	ds_read_b32 v24, v3
	ds_read_b32 v28, v5
	ds_read_b32 v25, v11
	ds_read_b32 v29, v29
	ds_read_b32 v30, v30
	ds_read_b32 v34, v31
	ds_read_b32 v31, v35
	ds_read_b32 v35, v7
	v_pk_fma_f32 v[6:7], v[6:7], v[26:27], 0 op_sel_hi:[0,1,0]
	v_pk_fma_f32 v[2:3], v[2:3], v[32:33], v[6:7] op_sel_hi:[0,1,1]
	s_waitcnt lgkmcnt(5)
	v_pk_fma_f32 v[22:23], v[10:11], v[24:25], v[22:23] op_sel_hi:[0,1,1]
	s_waitcnt lgkmcnt(1)
	v_pk_fma_f32 v[2:3], v[10:11], v[30:31], v[2:3] op_sel_hi:[0,1,1]
	v_pk_fma_f32 v[22:23], v[4:5], v[28:29], v[22:23] op_sel_hi:[0,1,1]
	s_waitcnt lgkmcnt(0)
	v_pk_fma_f32 v[2:3], v[4:5], v[34:35], v[2:3] op_sel_hi:[0,1,1]
	v_pk_mul_f32 v[8:9], v[8:9], v[0:1] op_sel_hi:[1,0]
	v_pk_mul_f32 v[12:13], v[0:1], v[12:13] op_sel_hi:[0,1]
	v_pk_mul_f32 v[14:15], v[0:1], v[14:15] op_sel_hi:[0,1]
	v_pk_mul_f32 v[16:17], v[0:1], v[16:17] op_sel_hi:[0,1]
	v_pk_mul_f32 v[18:19], v[0:1], v[18:19] op_sel_hi:[0,1]
	v_pk_mul_f32 v[20:21], v[0:1], v[20:21] op_sel_hi:[0,1]
	v_pk_mul_f32 v[22:23], v[0:1], v[22:23] op_sel_hi:[0,1]
	v_pk_mul_f32 v[2:3], v[0:1], v[2:3] op_sel_hi:[0,1]
	v_lshlrev_b32_e32 v0, 11, v147
	v_lshl_or_b32 v0, v82, 16, v0
	v_lshlrev_b32_e32 v6, 5, v154
	v_lshl_add_u64 v[4:5], s[0:1], 0, v[0:1]
	v_ashrrev_i32_e32 v7, 31, v6
	v_lshl_add_u64 v[4:5], v[6:7], 1, v[4:5]
	v_mov_b32_e32 v147, v1
	v_lshl_add_u64 v[4:5], v[4:5], 0, v[146:147]
	s_mov_b64 s[0:1], 0x4328400
	v_lshl_add_u64 v[6:7], v[4:5], 0, s[0:1]
	s_mov_b32 s0, 0x4328000
	v_add_co_u32_e32 v4, vcc, s0, v4
	v_cvt_pk_bf16_f32 v8, v8, v9
	v_cvt_pk_bf16_f32 v9, v12, v13
	v_addc_co_u32_e32 v5, vcc, 0, v5, vcc
	global_store_dwordx2 v[4:5], v[8:9], off offset:1024
	v_cvt_pk_bf16_f32 v4, v14, v15
	v_cvt_pk_bf16_f32 v5, v16, v17
	global_store_dwordx2 v[6:7], v[4:5], off offset:16
	v_cvt_pk_bf16_f32 v4, v18, v19
	v_cvt_pk_bf16_f32 v5, v20, v21
	global_store_dwordx2 v[6:7], v[4:5], off offset:32
	v_cvt_pk_bf16_f32 v4, v22, v23
	v_cvt_pk_bf16_f32 v5, v2, v3
	global_store_dwordx2 v[6:7], v[4:5], off offset:48
	s_barrier
	s_mov_b64 s[0:1], 0
